# mix-norm and final-norm row loops software-pipelined as well (all three norm loops prefetch one row ahead)
# baseline (speedup 1.0000x reference)
; __device__ __forceinline__ int opaque_tid() { int t = threadIdx.x; asm volatile("" : "+v"(t)); return t; }
; __device__ __forceinline__ unsigned pk_bf16(float lo, float hi) { f32x2_t v = {lo, hi}; bf16x2_t b = __builtin_convertvector(v, bf16x2_t); return __builtin_bit_cast(unsigned, b); }
; __device__ __forceinline__ void norm_phase(const float* src_real, const float* src_meta, const float* w, bf16_t* hn, int G) {
;     const int tid = opaque_tid(), lane = tid & 63, wid = __builtin_amdgcn_readfirstlane(tid >> 6);
;     const int gw = blockIdx.x * NWAVES + wid, NGW = G * NWAVES;
;     f32x4 wv[4];
; #pragma unroll
;     for (int j = 0; j < 4; ++j) wv[j] = ((const f32x4*)w)[lane + 64 * j];
;     for (int row = gw; row < MT; row += NGW) {
;         const float* xr = row < MR ? src_real + (size_t)row * DM : src_meta + (size_t)(row - MR) * DM;
;         f32x4 v[4]; float s = 0.f;
; #pragma unroll
;         for (int j = 0; j < 4; ++j) { v[j] = ((const f32x4*)xr)[lane + 64 * j]; s += (v[j].x * v[j].x + v[j].y * v[j].y) + (v[j].z * v[j].z + v[j].w * v[j].w); }
;         const float r = rsqrtf(wave_sum(s) * (1.f / DM) + EPS);
;         u32x2* o8 = (u32x2*)(hn + (size_t)row * DM) + lane;
; #pragma unroll
;         for (int j = 0; j < 4; ++j) { u32x2 o; o.x = pk_bf16(v[j].x * r * wv[j].x, v[j].y * r * wv[j].y); o.y = pk_bf16(v[j].z * r * wv[j].z, v[j].w * r * wv[j].w); o8[64 * j] = o; }
;     }
.LBB0_58:
	v_readlane_b32 s2, v254, 58
	v_readlane_b32 s3, v254, 59
	s_lshl_b32 s2, s2, 10
	s_ashr_i32 s3, s2, 31
	v_writelane_b32 v254, s2, 62
	v_mov_b32_e32 v0, v194
	s_nop 0
	v_writelane_b32 v254, s3, 63
	v_readfirstlane_b32 s2, v0
	s_ashr_i32 s2, s2, 6
	v_readlane_b32 s3, v253, 4
	s_add_i32 s18, s2, s3
	s_cmp_gt_i32 s18, 0x800f
	s_cbranch_scc1 .LBB0_63
	s_load_dwordx2 s[2:3], s[20:21], 0x10
	v_readlane_b32 s4, v254, 62
	v_readlane_b32 s5, v254, 63
	s_lshl_b64 s[4:5], s[4:5], 2
	v_and_b32_e32 v28, 63, v0
	s_waitcnt lgkmcnt(0)
	s_add_u32 s2, s2, s4
	v_lshlrev_b32_e32 v0, 4, v28
	s_addc_u32 s3, s3, s5
	global_load_dwordx4 v[2:5], v0, s[2:3] offset:3072
	global_load_dwordx4 v[6:9], v0, s[2:3] offset:2048
	global_load_dwordx4 v[10:13], v0, s[2:3] offset:1024
	global_load_dwordx4 v[18:21], v0, s[2:3]
	v_cmp_lt_i32_e32 vcc, v207, v201
	s_mov_b64 s[2:3], 0x6400000
	s_ashr_i32 s19, s18, 31
	v_cndmask_b32_e32 v0, v200, v207, vcc
	v_cmp_lt_i32_e32 vcc, v206, v201
	v_lshlrev_b32_e32 v17, 2, v0
	v_readlane_b32 s4, v254, 10
	v_cndmask_b32_e32 v0, v200, v206, vcc
	v_lshlrev_b32_e32 v22, 2, v0
	v_xor_b32_e32 v0, 4, v200
	v_cmp_lt_i32_e32 vcc, v0, v201
	v_readlane_b32 s5, v254, 11
	s_nop 0
	v_cndmask_b32_e32 v0, v200, v0, vcc
	v_lshlrev_b32_e32 v23, 2, v0
	v_xor_b32_e32 v0, 8, v200
	v_cmp_lt_i32_e32 vcc, v0, v201
	s_nop 1
	v_cndmask_b32_e32 v0, v200, v0, vcc
	v_lshlrev_b32_e32 v24, 2, v0
	v_xor_b32_e32 v0, 16, v200
	v_cmp_lt_i32_e32 vcc, v0, v201
	s_nop 1
	v_cndmask_b32_e32 v0, v200, v0, vcc
	v_lshlrev_b32_e32 v25, 2, v0
	v_xor_b32_e32 v0, 32, v200
	v_cmp_lt_i32_e32 vcc, v0, v201
	s_nop 1
	v_cndmask_b32_e32 v0, v200, v0, vcc
	v_lshlrev_b32_e32 v26, 2, v0
	v_lshlrev_b32_e32 v0, 3, v28
	v_lshl_add_u64 v[14:15], s[14:15], 0, v[0:1]
	v_lshl_add_u64 v[14:15], v[14:15], 0, s[2:3]
	s_lshl_b64 s[2:3], s[18:19], 12
	s_add_u32 s12, s12, s2
	s_addc_u32 s13, s13, s3
	v_lshlrev_b32_e32 v0, 4, v28
	s_mov_b32 s39, 0x800000
	s_mov_b32 s38, 0
	s_mov_b64 s[30:31], s[18:19]
	s_mov_b64 s[36:37], s[12:13]
	global_load_dwordx4 v[28:31], v0, s[36:37]
	global_load_dwordx4 v[32:35], v0, s[36:37] offset:1024
	global_load_dwordx4 v[36:39], v0, s[36:37] offset:2048
	global_load_dwordx4 v[40:43], v0, s[36:37] offset:3072
	s_add_u32 s18, s18, s88
	s_addc_u32 s19, s19, s89
	s_add_u32 s12, s12, s4
	s_addc_u32 s13, s13, s5
	s_add_i32 s34, s18, 0xffff8000
	s_mov_b32 s35, 0
	s_lshl_b64 s[34:35], s[34:35], 12
	s_add_u32 s34, s16, s34
	s_addc_u32 s35, s17, s35
	s_cmp_lt_i32 s18, 0x8000
	s_cselect_b64 s[36:37], s[12:13], s[34:35]
	s_mov_b64 s[32:33], s[18:19]
	global_load_dwordx4 v[60:63], v0, s[36:37]
	global_load_dwordx4 v[64:67], v0, s[36:37] offset:1024
	global_load_dwordx4 v[68:71], v0, s[36:37] offset:2048
	global_load_dwordx4 v[72:75], v0, s[36:37] offset:3072
	s_waitcnt vmcnt(4)
	s_branch .Lmixnorm_procA
.Lmixnorm_loop:
	s_add_u32 s18, s18, s88
	s_addc_u32 s19, s19, s89
	s_add_u32 s12, s12, s4
	s_addc_u32 s13, s13, s5
	s_cmp_lt_i32 s18, 0x8010
	s_cbranch_scc0 .Lmixnorm_lastB
	s_add_i32 s34, s18, 0xffff8000
	s_mov_b32 s35, 0
	s_lshl_b64 s[34:35], s[34:35], 12
	s_add_u32 s34, s16, s34
	s_addc_u32 s35, s17, s35
	s_cmp_lt_i32 s18, 0x8000
	s_cselect_b64 s[36:37], s[12:13], s[34:35]
	s_mov_b64 s[30:31], s[18:19]
	global_load_dwordx4 v[28:31], v0, s[36:37]
	global_load_dwordx4 v[32:35], v0, s[36:37] offset:1024
	global_load_dwordx4 v[36:39], v0, s[36:37] offset:2048
	global_load_dwordx4 v[40:43], v0, s[36:37] offset:3072
	s_waitcnt vmcnt(8)
; __device__ __forceinline__ unsigned pk_bf16(float lo, float hi) { f32x2_t v = {lo, hi}; bf16x2_t b = __builtin_convertvector(v, bf16x2_t); return __builtin_bit_cast(unsigned, b); }
; __device__ __forceinline__ void norm_phase(const float* src_real, const float* src_meta, const float* w, bf16_t* hn, int G) {
;     ...
;     for (int row = gw; row < MT; row += NGW) {
;         const float* xr = row < MR ? src_real + (size_t)row * DM : src_meta + (size_t)(row - MR) * DM;
;         f32x4 v[4]; float s = 0.f;
; #pragma unroll
;         for (int j = 0; j < 4; ++j) { v[j] = ((const f32x4*)xr)[lane + 64 * j]; s += (v[j].x * v[j].x + v[j].y * v[j].y) + (v[j].z * v[j].z + v[j].w * v[j].w); }
;         const float r = rsqrtf(wave_sum(s) * (1.f / DM) + EPS);
;         u32x2* o8 = (u32x2*)(hn + (size_t)row * DM) + lane;
; #pragma unroll
;         for (int j = 0; j < 4; ++j) { u32x2 o; o.x = pk_bf16(v[j].x * r * wv[j].x, v[j].y * r * wv[j].y); o.y = pk_bf16(v[j].z * r * wv[j].z, v[j].w * r * wv[j].w); o8[64 * j] = o; }
;     }
.Lmixnorm_procB:
	v_mul_f32_e32 v76, v60, v60
	v_mul_f32_e32 v77, v64, v64
	v_mul_f32_e32 v78, v68, v68
	v_mul_f32_e32 v79, v72, v72
	v_fmac_f32_e32 v76, v61, v61
	v_fmac_f32_e32 v77, v65, v65
	v_fmac_f32_e32 v78, v69, v69
	v_fmac_f32_e32 v79, v73, v73
	v_fmac_f32_e32 v76, v62, v62
	v_fmac_f32_e32 v77, v66, v66
	v_fmac_f32_e32 v78, v70, v70
	v_fmac_f32_e32 v79, v74, v74
	v_fmac_f32_e32 v76, v63, v63
	v_fmac_f32_e32 v77, v67, v67
	v_fmac_f32_e32 v78, v71, v71
	v_fmac_f32_e32 v79, v75, v75
	v_add_f32_e32 v76, v76, v77
	v_add_f32_e32 v78, v78, v79
	s_lshl_b64 s[34:35], s[32:33], 11
	v_add_f32_e32 v27, v76, v78
	ds_bpermute_b32 v44, v17, v27
	s_waitcnt lgkmcnt(0)
	v_add_f32_e32 v27, v27, v44
	ds_bpermute_b32 v44, v22, v27
	s_waitcnt lgkmcnt(0)
	v_add_f32_e32 v27, v27, v44
	ds_bpermute_b32 v44, v23, v27
	s_waitcnt lgkmcnt(0)
	v_add_f32_e32 v27, v27, v44
	ds_bpermute_b32 v44, v24, v27
	s_waitcnt lgkmcnt(0)
	v_add_f32_e32 v27, v27, v44
	ds_bpermute_b32 v44, v25, v27
	s_waitcnt lgkmcnt(0)
	v_add_f32_e32 v27, v27, v44
	ds_bpermute_b32 v44, v26, v27
	s_waitcnt lgkmcnt(0)
	v_add_f32_e32 v27, v27, v44
	v_fmamk_f32 v27, v27, 0x3a800000, v195
	v_cmp_gt_f32_e32 vcc, s39, v27
	v_mul_f32_e32 v44, 0x4b800000, v27
	v_lshl_add_u64 v[46:47], v[14:15], 0, s[34:35]
	s_nop 0
	v_cndmask_b32_e32 v27, v27, v44, vcc
	v_rsq_f32_e32 v27, v27
	s_nop 0
	v_mul_f32_e32 v44, 0x45800000, v27
	v_cndmask_b32_e32 v44, v27, v44, vcc
	v_pk_mul_f32 v[60:61], v[60:61], v[44:45] op_sel_hi:[1,0]
	v_pk_mul_f32 v[62:63], v[62:63], v[44:45] op_sel_hi:[1,0]
	v_pk_mul_f32 v[64:65], v[64:65], v[44:45] op_sel_hi:[1,0]
	v_pk_mul_f32 v[66:67], v[66:67], v[44:45] op_sel_hi:[1,0]
	v_pk_mul_f32 v[68:69], v[68:69], v[44:45] op_sel_hi:[1,0]
	v_pk_mul_f32 v[70:71], v[70:71], v[44:45] op_sel_hi:[1,0]
	v_pk_mul_f32 v[72:73], v[72:73], v[44:45] op_sel_hi:[1,0]
	v_pk_mul_f32 v[74:75], v[74:75], v[44:45] op_sel_hi:[1,0]
	v_pk_mul_f32 v[60:61], v[18:19], v[60:61]
	v_pk_mul_f32 v[62:63], v[20:21], v[62:63]
	v_pk_mul_f32 v[64:65], v[10:11], v[64:65]
	v_pk_mul_f32 v[66:67], v[12:13], v[66:67]
	v_pk_mul_f32 v[68:69], v[6:7], v[68:69]
	v_pk_mul_f32 v[70:71], v[8:9], v[70:71]
	v_pk_mul_f32 v[72:73], v[2:3], v[72:73]
	v_pk_mul_f32 v[74:75], v[4:5], v[74:75]
	v_cvt_pk_bf16_f32 v60, v60, v61
	v_cvt_pk_bf16_f32 v61, v62, v63
	v_cvt_pk_bf16_f32 v64, v64, v65
	v_cvt_pk_bf16_f32 v65, v66, v67
	v_cvt_pk_bf16_f32 v68, v68, v69
	v_cvt_pk_bf16_f32 v69, v70, v71
	v_cvt_pk_bf16_f32 v72, v72, v73
	v_cvt_pk_bf16_f32 v73, v74, v75
	global_store_dwordx2 v[46:47], v[60:61], off
	global_store_dwordx2 v[46:47], v[64:65], off offset:512
	global_store_dwordx2 v[46:47], v[68:69], off offset:1024
	global_store_dwordx2 v[46:47], v[72:73], off offset:1536
	s_cmp_lg_u32 s38, 0
	s_cbranch_scc1 .Lmixnorm_done
	s_add_u32 s18, s18, s88
	s_addc_u32 s19, s19, s89
	s_add_u32 s12, s12, s4
	s_addc_u32 s13, s13, s5
	s_cmp_lt_i32 s18, 0x8010
	s_cbranch_scc0 .Lmixnorm_lastA
	s_add_i32 s34, s18, 0xffff8000
	s_mov_b32 s35, 0
	s_lshl_b64 s[34:35], s[34:35], 12
	s_add_u32 s34, s16, s34
	s_addc_u32 s35, s17, s35
	s_cmp_lt_i32 s18, 0x8000
	s_cselect_b64 s[36:37], s[12:13], s[34:35]
	s_mov_b64 s[32:33], s[18:19]
	global_load_dwordx4 v[60:63], v0, s[36:37]
	global_load_dwordx4 v[64:67], v0, s[36:37] offset:1024
	global_load_dwordx4 v[68:71], v0, s[36:37] offset:2048
	global_load_dwordx4 v[72:75], v0, s[36:37] offset:3072
	s_waitcnt vmcnt(8)
.Lmixnorm_procA:
	v_mul_f32_e32 v76, v28, v28
	v_mul_f32_e32 v77, v32, v32
	v_mul_f32_e32 v78, v36, v36
	v_mul_f32_e32 v79, v40, v40
	v_fmac_f32_e32 v76, v29, v29
	v_fmac_f32_e32 v77, v33, v33
	v_fmac_f32_e32 v78, v37, v37
	v_fmac_f32_e32 v79, v41, v41
	v_fmac_f32_e32 v76, v30, v30
	v_fmac_f32_e32 v77, v34, v34
	v_fmac_f32_e32 v78, v38, v38
	v_fmac_f32_e32 v79, v42, v42
	v_fmac_f32_e32 v76, v31, v31
	v_fmac_f32_e32 v77, v35, v35
	v_fmac_f32_e32 v78, v39, v39
	v_fmac_f32_e32 v79, v43, v43
	v_add_f32_e32 v76, v76, v77
	v_add_f32_e32 v78, v78, v79
	s_lshl_b64 s[34:35], s[30:31], 11
	v_add_f32_e32 v27, v76, v78
	ds_bpermute_b32 v44, v17, v27
	s_waitcnt lgkmcnt(0)
	v_add_f32_e32 v27, v27, v44
	ds_bpermute_b32 v44, v22, v27
	s_waitcnt lgkmcnt(0)
	v_add_f32_e32 v27, v27, v44
	ds_bpermute_b32 v44, v23, v27
	s_waitcnt lgkmcnt(0)
	v_add_f32_e32 v27, v27, v44
	ds_bpermute_b32 v44, v24, v27
	s_waitcnt lgkmcnt(0)
	v_add_f32_e32 v27, v27, v44
	ds_bpermute_b32 v44, v25, v27
	s_waitcnt lgkmcnt(0)
	v_add_f32_e32 v27, v27, v44
	ds_bpermute_b32 v44, v26, v27
	s_waitcnt lgkmcnt(0)
	v_add_f32_e32 v27, v27, v44
	v_fmamk_f32 v27, v27, 0x3a800000, v195
	v_cmp_gt_f32_e32 vcc, s39, v27
	v_mul_f32_e32 v44, 0x4b800000, v27
	v_lshl_add_u64 v[46:47], v[14:15], 0, s[34:35]
	s_nop 0
	v_cndmask_b32_e32 v27, v27, v44, vcc
	v_rsq_f32_e32 v27, v27
	s_nop 0
	v_mul_f32_e32 v44, 0x45800000, v27
	v_cndmask_b32_e32 v44, v27, v44, vcc
	v_pk_mul_f32 v[28:29], v[28:29], v[44:45] op_sel_hi:[1,0]
	v_pk_mul_f32 v[30:31], v[30:31], v[44:45] op_sel_hi:[1,0]
	v_pk_mul_f32 v[32:33], v[32:33], v[44:45] op_sel_hi:[1,0]
	v_pk_mul_f32 v[34:35], v[34:35], v[44:45] op_sel_hi:[1,0]
	v_pk_mul_f32 v[36:37], v[36:37], v[44:45] op_sel_hi:[1,0]
	v_pk_mul_f32 v[38:39], v[38:39], v[44:45] op_sel_hi:[1,0]
	v_pk_mul_f32 v[40:41], v[40:41], v[44:45] op_sel_hi:[1,0]
	v_pk_mul_f32 v[42:43], v[42:43], v[44:45] op_sel_hi:[1,0]
	v_pk_mul_f32 v[28:29], v[18:19], v[28:29]
	v_pk_mul_f32 v[30:31], v[20:21], v[30:31]
	v_pk_mul_f32 v[32:33], v[10:11], v[32:33]
	v_pk_mul_f32 v[34:35], v[12:13], v[34:35]
	v_pk_mul_f32 v[36:37], v[6:7], v[36:37]
	v_pk_mul_f32 v[38:39], v[8:9], v[38:39]
	v_pk_mul_f32 v[40:41], v[2:3], v[40:41]
	v_pk_mul_f32 v[42:43], v[4:5], v[42:43]
	v_cvt_pk_bf16_f32 v28, v28, v29
	v_cvt_pk_bf16_f32 v29, v30, v31
	v_cvt_pk_bf16_f32 v32, v32, v33
	v_cvt_pk_bf16_f32 v33, v34, v35
	v_cvt_pk_bf16_f32 v36, v36, v37
	v_cvt_pk_bf16_f32 v37, v38, v39
	v_cvt_pk_bf16_f32 v40, v40, v41
	v_cvt_pk_bf16_f32 v41, v42, v43
	global_store_dwordx2 v[46:47], v[28:29], off
	global_store_dwordx2 v[46:47], v[32:33], off offset:512
	global_store_dwordx2 v[46:47], v[36:37], off offset:1024
	global_store_dwordx2 v[46:47], v[40:41], off offset:1536
	s_cmp_lg_u32 s38, 0
	s_cbranch_scc1 .Lmixnorm_done
	s_branch .Lmixnorm_loop
.Lmixnorm_lastB:
	s_mov_b32 s38, 1
	s_waitcnt vmcnt(4)
	s_branch .Lmixnorm_procB

; __device__ __forceinline__ void xcd_barrier(const XcdBarrier& b) {
;     asm volatile("s_waitcnt vmcnt(0)" ::: "memory");
;     __syncthreads();
;     if (threadIdx.x == 0) {
;         unsigned* bar = b.bar;
;         __builtin_amdgcn_s_waitcnt(0);
;         unsigned nloc = b.st[0], nx = b.st[1];
;         if (nloc == 0u) { xcd_barrier_complete(bar, b.x, nloc, nx); b.st[0] = nloc; b.st[1] = nx; }
.Lmixnorm_done:
.LBB0_63:
	s_mov_b64 s[12:13], -1
	s_and_b64 vcc, exec, s[10:11]
	s_cbranch_vccz .LBB0_117
	s_mov_b64 s[12:13], s[90:91]
	s_getreg_b32 s2, hwreg(HW_REG_XCC_ID, 0, 4)
	s_waitcnt vmcnt(0)
	s_waitcnt lgkmcnt(0)
	s_barrier
	s_mov_b64 s[10:11], exec
	v_readlane_b32 s4, v253, 2
	v_readlane_b32 s5, v253, 3
	s_and_b64 s[4:5], s[10:11], s[4:5]
	s_mov_b64 exec, s[4:5]
	s_cbranch_execz .LBB0_116
	v_readlane_b32 s3, v254, 43
	s_load_dwordx2 s[12:13], s[12:13], 0x88
	s_waitcnt vmcnt(0) expcnt(0) lgkmcnt(0)
	v_mov_b32_e32 v0, s3
	ds_read_b32 v3, v0
	v_readlane_b32 s3, v254, 44
	s_and_b32 s2, s2, 15
	s_waitcnt lgkmcnt(0)
	v_cmp_ne_u32_e32 vcc, 0, v3
	v_mov_b32_e32 v0, s3
	ds_read_b32 v2, v0
	s_cbranch_vccnz .LBB0_80
	s_add_u32 s14, s12, 0x1000
	s_addc_u32 s15, s13, 0
	s_add_u32 s16, s12, 0x1100
	s_addc_u32 s17, s13, 0
	s_add_u32 s18, s12, 0x1200
	s_addc_u32 s19, s13, 0
	s_add_u32 s20, s12, 0x1300
	s_addc_u32 s21, s13, 0
	s_mov_b32 s3, 1
	s_branch .LBB0_68

; #define LAS __attribute__((address_space(3)))
; #define VFR(F, s4) _Pragma("unroll") for (int i = 0; i < 4; ++i) F[i] = *(const LAS bf16x8*)(Vb + (2 * (s4) + hi) * 2048 + (32 * i + l31) * 16)
; #define KFR(F, dh) _Pragma("unroll") for (int i = 0; i < 4; ++i) F[i] = *(const LAS bf16x8*)(Kb + (c * 8 + 2 * (2 * (dh) + (i >> 1)) + hi) * 1024 + (32 * (i & 1) + kvrow) * 16)
; #define PVM(F, s4) _Pragma("unroll") for (int i = 0; i < 4; ++i) o[i] = __builtin_amdgcn_mfma_f32_32x32x16_bf16(F[i], __builtin_bit_cast(bf16x8, pk[s4]), o[i], 0, 0, 0)
; #define QKM(F, dh) _Pragma("unroll") for (int i = 0; i < 2; ++i) { sA = __builtin_amdgcn_mfma_f32_32x32x16_bf16(F[2 * i], qf[2 * (dh) + i], sA, 0, 0, 0); sB = __builtin_amdgcn_mfma_f32_32x32x16_bf16(F[2 * i + 1], qf[2 * (dh) + i], sB, 0, 0, 0); }
; #define SBAR __builtin_amdgcn_sched_barrier(0)
; #define SBAR __builtin_amdgcn_sched_barrier(0)
; __device__ __forceinline__ void attn_phase(LAS unsigned char* lds, const bf16_t* Q, const bf16_t* Kimg, const bf16_t* Vimg, const bf16_t* Kmeta, const bf16_t* Vmeta,
;                                            bf16_t* O, const float* lamp, const float* sublnw, float lambda_init, int G) {
;     ...
;                 if (active) {
;                     const LAS unsigned char* Vb = lds + 65536 + (j & 3) * 16384;
;                     const LAS unsigned char* Kb = lds + ((j + 1) & 3) * 16384;
;                     bf16x8 fa[4], fb[4];
;     ...
;                     __builtin_amdgcn_s_setprio(1);
;                     VFR(fa, 0);
;                     if (__any(alpha != 1.f)) {
; #pragma unroll
;                         for (int d = 0; d < 4; ++d)
; #pragma unroll
;                             for (int r = 0; r < 16; ++r) o[d][r] *= alpha;
;                     }
;                     SBAR; VFR(fb, 1); SBAR; PVM(fa, 0); SBAR; VFR(fa, 2); SBAR; PVM(fb, 1); SBAR; VFR(fb, 3); SBAR; PVM(fa, 2); SBAR; KFR(fa, 0); SBAR; PVM(fb, 3); SBAR; KFR(fb, 1);
;                     { const int kp0_ = 16 + 64 * j; const float tb_ = slope2 * (float)(kp0_ - qpos0 + 8 * hi) - mrun;
; #pragma unroll
;                       for (int r = 0; r < 16; ++r) { sA[r] = fmaf(slope2, (float)(16 * (r >> 3) + (r & 7)), tb_); sB[r] = fmaf(slope2, (float)(32 + 16 * (r >> 3) + (r & 7)), tb_); } }
;                     SBAR; QKM(fa, 0); SBAR; QKM(fb, 1);
.LBB0_766:
	s_and_b64 vcc, exec, s[30:31]
	s_cbranch_vccnz .LBB0_770
	s_add_i32 s10, s38, 0x4000
	s_and_b32 s10, s10, 0xc000
	s_nop 0
	v_add_u32_e32 v22, s10, v220
	ds_read_b128 v[18:21], v22
	ds_read_b128 v[10:13], v22 offset:512
	ds_read_b128 v[6:9], v22 offset:1024
	ds_read_b128 v[2:5], v22 offset:1536
	v_cmp_neq_f32_e32 vcc, 1.0, v178
	s_cbranch_vccz .LBB0_769
	v_pk_mul_f32 v[112:113], v[112:113], v[178:179] op_sel_hi:[1,0]
	v_pk_mul_f32 v[110:111], v[110:111], v[178:179] op_sel_hi:[1,0]
	v_pk_mul_f32 v[108:109], v[108:109], v[178:179] op_sel_hi:[1,0]
	v_pk_mul_f32 v[106:107], v[106:107], v[178:179] op_sel_hi:[1,0]
	v_pk_mul_f32 v[104:105], v[104:105], v[178:179] op_sel_hi:[1,0]
	v_pk_mul_f32 v[102:103], v[102:103], v[178:179] op_sel_hi:[1,0]
	v_pk_mul_f32 v[100:101], v[100:101], v[178:179] op_sel_hi:[1,0]
	v_pk_mul_f32 v[98:99], v[98:99], v[178:179] op_sel_hi:[1,0]
	v_pk_mul_f32 v[96:97], v[96:97], v[178:179] op_sel_hi:[1,0]
	v_pk_mul_f32 v[94:95], v[94:95], v[178:179] op_sel_hi:[1,0]
	v_pk_mul_f32 v[92:93], v[92:93], v[178:179] op_sel_hi:[1,0]
	v_pk_mul_f32 v[90:91], v[90:91], v[178:179] op_sel_hi:[1,0]
	v_pk_mul_f32 v[88:89], v[88:89], v[178:179] op_sel_hi:[1,0]
	v_pk_mul_f32 v[86:87], v[86:87], v[178:179] op_sel_hi:[1,0]
	v_pk_mul_f32 v[84:85], v[84:85], v[178:179] op_sel_hi:[1,0]
	v_pk_mul_f32 v[82:83], v[82:83], v[178:179] op_sel_hi:[1,0]
	v_pk_mul_f32 v[80:81], v[80:81], v[178:179] op_sel_hi:[1,0]
	v_pk_mul_f32 v[78:79], v[78:79], v[178:179] op_sel_hi:[1,0]
	v_pk_mul_f32 v[76:77], v[76:77], v[178:179] op_sel_hi:[1,0]
	v_pk_mul_f32 v[74:75], v[74:75], v[178:179] op_sel_hi:[1,0]
	v_pk_mul_f32 v[72:73], v[72:73], v[178:179] op_sel_hi:[1,0]
	v_pk_mul_f32 v[70:71], v[70:71], v[178:179] op_sel_hi:[1,0]
	v_pk_mul_f32 v[68:69], v[68:69], v[178:179] op_sel_hi:[1,0]
	v_pk_mul_f32 v[66:67], v[66:67], v[178:179] op_sel_hi:[1,0]
	v_pk_mul_f32 v[64:65], v[64:65], v[178:179] op_sel_hi:[1,0]
	v_pk_mul_f32 v[62:63], v[62:63], v[178:179] op_sel_hi:[1,0]
	v_pk_mul_f32 v[60:61], v[60:61], v[178:179] op_sel_hi:[1,0]
	v_pk_mul_f32 v[58:59], v[58:59], v[178:179] op_sel_hi:[1,0]
	v_pk_mul_f32 v[56:57], v[56:57], v[178:179] op_sel_hi:[1,0]
	v_pk_mul_f32 v[54:55], v[54:55], v[178:179] op_sel_hi:[1,0]
	v_pk_mul_f32 v[52:53], v[52:53], v[178:179] op_sel_hi:[1,0]
	v_pk_mul_f32 v[50:51], v[50:51], v[178:179] op_sel_hi:[1,0]
.LBB0_769:
	s_add_i32 s10, s38, 0x8000
	s_and_b32 s10, s10, 0xc000
	ds_read_b128 v[24:27], v22 offset:4096
	ds_read_b128 v[28:31], v22 offset:4608
	ds_read_b128 v[32:35], v22 offset:5120
	ds_read_b128 v[36:39], v22 offset:5632
	s_waitcnt lgkmcnt(7)
	v_mfma_f32_32x32x16_bf16 v[98:113], v[18:21], v[138:141], v[98:113]
	s_waitcnt lgkmcnt(6)
	v_mfma_f32_32x32x16_bf16 v[82:97], v[10:13], v[138:141], v[82:97]
	s_waitcnt lgkmcnt(5)
	v_mfma_f32_32x32x16_bf16 v[66:81], v[6:9], v[138:141], v[66:81]
	s_waitcnt lgkmcnt(4)
	v_mfma_f32_32x32x16_bf16 v[50:65], v[2:5], v[138:141], v[50:65]
	ds_read_b128 v[2:5], v22 offset:8192
	ds_read_b128 v[6:9], v22 offset:8704
	ds_read_b128 v[10:13], v22 offset:9216
	ds_read_b128 v[18:21], v22 offset:9728
	s_waitcnt lgkmcnt(7)
	v_mfma_f32_32x32x16_bf16 v[98:113], v[24:27], v[142:145], v[98:113]
	s_waitcnt lgkmcnt(6)
	v_mfma_f32_32x32x16_bf16 v[82:97], v[28:31], v[142:145], v[82:97]
	s_waitcnt lgkmcnt(5)
	v_mfma_f32_32x32x16_bf16 v[66:81], v[32:35], v[142:145], v[66:81]
	s_waitcnt lgkmcnt(4)
	v_mfma_f32_32x32x16_bf16 v[50:65], v[36:39], v[142:145], v[50:65]
	ds_read_b128 v[24:27], v22 offset:12288
	ds_read_b128 v[28:31], v22 offset:12800
	ds_read_b128 v[32:35], v22 offset:13312
	ds_read_b128 v[36:39], v22 offset:13824
	s_waitcnt lgkmcnt(7)
	v_mfma_f32_32x32x16_bf16 v[98:113], v[2:5], v[134:137], v[98:113]
	s_waitcnt lgkmcnt(6)
	v_mfma_f32_32x32x16_bf16 v[82:97], v[6:9], v[134:137], v[82:97]
	s_waitcnt lgkmcnt(5)
	v_mfma_f32_32x32x16_bf16 v[66:81], v[10:13], v[134:137], v[66:81]
	s_waitcnt lgkmcnt(4)
	v_mfma_f32_32x32x16_bf16 v[50:65], v[18:21], v[134:137], v[50:65]
	v_add_u32_e32 v18, s10, v221
	ds_read_b128 v[2:5], v18
	ds_read_b128 v[6:9], v18 offset:512
	ds_read_b128 v[10:13], v18 offset:2048
	ds_read_b128 v[184:187], v18 offset:2560
	s_waitcnt lgkmcnt(7)
	v_mfma_f32_32x32x16_bf16 v[98:113], v[24:27], v[146:149], v[98:113]
	s_waitcnt lgkmcnt(6)
	v_mfma_f32_32x32x16_bf16 v[82:97], v[28:31], v[146:149], v[82:97]
	s_waitcnt lgkmcnt(5)
	v_mfma_f32_32x32x16_bf16 v[66:81], v[32:35], v[146:149], v[66:81]
	s_waitcnt lgkmcnt(4)
	v_mfma_f32_32x32x16_bf16 v[50:65], v[36:39], v[146:149], v[50:65]
	v_cvt_f32_i32_e32 v19, v179
	s_mov_b32 s10, 2.0
	s_mov_b32 s11, 0x40400000
	ds_read_b128 v[188:191], v18 offset:4096
	ds_read_b128 v[202:205], v18 offset:4608
	ds_read_b128 v[246:249], v18 offset:6144
	ds_read_b128 v[196:199], v18 offset:6656
	v_fma_f32 v34, v176, v19, -v173
	v_pk_fma_f32 v[20:21], v[14:15], s[10:11], v[34:35] op_sel_hi:[1,1,0]
	s_mov_b32 s10, 0x40c00000
	s_mov_b32 s11, 0x40e00000
	v_pk_fma_f32 v[24:25], v[14:15], s[10:11], v[34:35] op_sel_hi:[1,1,0]
	s_mov_b32 s10, 0x41900000
	s_mov_b32 s11, 0x41980000
	v_pk_fma_f32 v[28:29], v[14:15], s[10:11], v[34:35] op_sel_hi:[1,1,0]
	s_mov_b32 s10, 0x41b00000
	s_mov_b32 s11, 0x41b80000
	v_pk_fma_f32 v[32:33], v[14:15], s[10:11], v[34:35] op_sel_hi:[1,1,0]
	s_mov_b32 s10, 0x42500000
	v_mov_b32_e32 v177, v176
	s_mov_b32 s11, 0x42540000
	v_fma_f32 v18, 0, v176, v34
	v_add_f32_e32 v19, v176, v34
	v_pk_fma_f32 v[22:23], v[14:15], s[46:47], v[34:35] op_sel_hi:[1,1,0]
	v_pk_fma_f32 v[26:27], v[14:15], s[48:49], v[34:35] op_sel_hi:[1,1,0]
	v_pk_fma_f32 v[30:31], v[14:15], s[50:51], v[34:35] op_sel_hi:[1,1,0]
	v_pk_fma_f32 v[48:49], v[176:177], s[0:1], v[34:35] op_sel_hi:[1,1,0]
	v_pk_fma_f32 v[46:47], v[176:177], s[10:11], v[34:35] op_sel_hi:[1,1,0]
	v_pk_fma_f32 v[44:45], v[176:177], s[52:53], v[34:35] op_sel_hi:[1,1,0]
	v_pk_fma_f32 v[42:43], v[176:177], s[54:55], v[34:35] op_sel_hi:[1,1,0]
	v_pk_fma_f32 v[40:41], v[176:177], s[56:57], v[34:35] op_sel_hi:[1,1,0]
	v_pk_fma_f32 v[38:39], v[176:177], s[58:59], v[34:35] op_sel_hi:[1,1,0]
	v_pk_fma_f32 v[36:37], v[176:177], s[60:61], v[34:35] op_sel_hi:[1,1,0]
	v_pk_fma_f32 v[34:35], v[180:181], s[62:63], v[34:35] op_sel_hi:[1,1,0]
	s_waitcnt lgkmcnt(7)
	v_mfma_f32_32x32x16_bf16 v[18:33], v[2:5], v[118:121], v[18:33]
	s_waitcnt lgkmcnt(6)
	v_mfma_f32_32x32x16_bf16 v[34:49], v[6:9], v[118:121], v[34:49]
	s_waitcnt lgkmcnt(5)
	v_mfma_f32_32x32x16_bf16 v[18:33], v[10:13], v[122:125], v[18:33]
	s_waitcnt lgkmcnt(4)
	v_mfma_f32_32x32x16_bf16 v[34:49], v[184:187], v[122:125], v[34:49]
	s_waitcnt lgkmcnt(3)
	v_mfma_f32_32x32x16_bf16 v[18:33], v[188:191], v[126:129], v[18:33]
	s_waitcnt lgkmcnt(2)
	v_mfma_f32_32x32x16_bf16 v[34:49], v[202:205], v[126:129], v[34:49]
	s_waitcnt lgkmcnt(1)
	v_mfma_f32_32x32x16_bf16 v[18:33], v[246:249], v[130:133], v[18:33]
	s_waitcnt lgkmcnt(0)
	v_mfma_f32_32x32x16_bf16 v[34:49], v[196:199], v[130:133], v[34:49]
	s_nop 0

; __device__ __forceinline__ int opaque_tid() { int t = threadIdx.x; asm volatile("" : "+v"(t)); return t; }
; __device__ __forceinline__ void final_norm_phase(float* h, const float* w, int G) {
;     const int tid = opaque_tid(), lane = tid & 63, wid = __builtin_amdgcn_readfirstlane(tid >> 6);
;     const int gw = blockIdx.x * NWAVES + wid, NGW = G * NWAVES;
;     f32x4 wv[4];
; #pragma unroll
;     for (int j = 0; j < 4; ++j) wv[j] = ((const f32x4*)w)[lane + 64 * j];
;     for (int row = gw; row < MR; row += NGW) {
;         f32x4* xr = (f32x4*)(h + (size_t)row * DM);
;         f32x4 v[4]; float s = 0.f;
; #pragma unroll
;         for (int j = 0; j < 4; ++j) { v[j] = xr[lane + 64 * j]; s += (v[j].x * v[j].x + v[j].y * v[j].y) + (v[j].z * v[j].z + v[j].w * v[j].w); }
;         const float r = rsqrtf(wave_sum(s) * (1.f / DM) + EPS);
; #pragma unroll
;         for (int j = 0; j < 4; ++j) xr[lane + 64 * j] = v[j] * r * wv[j];
;     }
; }
.LBB0_1127:
	v_readlane_b32 s1, v253, 4
	v_readfirstlane_b32 s0, v194
	s_ashr_i32 s0, s0, 6
	s_add_i32 s0, s0, s1
	s_cmpk_gt_i32 s0, 0x7fff
	s_cbranch_scc1 .LBB0_1130
	s_load_dwordx4 s[4:7], s[90:91], 0x78
	v_and_b32_e32 v0, 63, v194
	v_lshlrev_b32_e32 v16, 4, v0
	v_mov_b32_e32 v17, 0
	v_cmp_lt_i32_e32 vcc, v207, v201
	v_xor_b32_e32 v20, 4, v200
	v_xor_b32_e32 v21, 8, v200
	v_cndmask_b32_e32 v18, v200, v207, vcc
	v_cmp_lt_i32_e32 vcc, v206, v201
	v_xor_b32_e32 v22, 16, v200
	v_xor_b32_e32 v23, 32, v200
	v_cndmask_b32_e32 v19, v200, v206, vcc
	v_cmp_lt_i32_e32 vcc, v20, v201
	s_ashr_i32 s1, s0, 31
	s_nop 0
	v_cndmask_b32_e32 v20, v200, v20, vcc
	v_cmp_lt_i32_e32 vcc, v21, v201
	s_lshl_b64 s[2:3], s[0:1], 12
	s_nop 0
	v_cndmask_b32_e32 v21, v200, v21, vcc
	v_cmp_lt_i32_e32 vcc, v22, v201
	s_nop 1
	v_cndmask_b32_e32 v22, v200, v22, vcc
	v_cmp_lt_i32_e32 vcc, v23, v201
	s_nop 1
	v_cndmask_b32_e32 v23, v200, v23, vcc
	v_lshlrev_b32_e32 v18, 2, v18
	v_lshlrev_b32_e32 v19, 2, v19
	v_lshlrev_b32_e32 v20, 2, v20
	v_lshlrev_b32_e32 v21, 2, v21
	v_lshlrev_b32_e32 v22, 2, v22
	v_lshlrev_b32_e32 v23, 2, v23
	v_mov_b32_e32 v24, 0x358637bd
	s_waitcnt lgkmcnt(0)
	global_load_dwordx4 v[0:3], v16, s[4:5]
	global_load_dwordx4 v[4:7], v16, s[4:5] offset:1024
	global_load_dwordx4 v[8:11], v16, s[4:5] offset:2048
	global_load_dwordx4 v[12:15], v16, s[4:5] offset:3072
	s_add_u32 s8, s6, s2
	s_addc_u32 s9, s7, s3
	v_lshl_add_u64 v[46:47], s[6:7], 0, v[16:17]
	v_readlane_b32 s10, v254, 10
	v_readlane_b32 s11, v254, 11
	s_mov_b32 s21, 0x800000
	s_mov_b32 s20, 0
	s_mov_b64 s[12:13], s[0:1]
	s_mov_b64 s[18:19], s[8:9]
	global_load_dwordx4 v[26:29], v16, s[18:19]
	global_load_dwordx4 v[30:33], v16, s[18:19] offset:1024
	global_load_dwordx4 v[34:37], v16, s[18:19] offset:2048
	global_load_dwordx4 v[38:41], v16, s[18:19] offset:3072
	s_add_u32 s0, s0, s88
	s_addc_u32 s1, s1, s89
	s_add_u32 s8, s8, s10
	s_addc_u32 s9, s9, s11
	s_mov_b64 s[18:19], s[8:9]
	s_mov_b64 s[14:15], s[0:1]
	global_load_dwordx4 v[60:63], v16, s[18:19]
	global_load_dwordx4 v[64:67], v16, s[18:19] offset:1024
	global_load_dwordx4 v[68:71], v16, s[18:19] offset:2048
	global_load_dwordx4 v[72:75], v16, s[18:19] offset:3072
	s_waitcnt vmcnt(4)
	s_branch .Lfinalnorm_procA
.Lfinalnorm_loop:
	s_add_u32 s0, s0, s88
	s_addc_u32 s1, s1, s89
	s_add_u32 s8, s8, s10
	s_addc_u32 s9, s9, s11
	s_cmp_lt_i32 s0, 0x8000
	s_cbranch_scc0 .Lfinalnorm_lastB
	s_mov_b64 s[18:19], s[8:9]
	s_mov_b64 s[12:13], s[0:1]
	global_load_dwordx4 v[26:29], v16, s[18:19]
	global_load_dwordx4 v[30:33], v16, s[18:19] offset:1024
	global_load_dwordx4 v[34:37], v16, s[18:19] offset:2048
	global_load_dwordx4 v[38:41], v16, s[18:19] offset:3072
	s_waitcnt vmcnt(8)
; __device__ __forceinline__ void final_norm_phase(float* h, const float* w, int G) {
;     ...
;     for (int row = gw; row < MR; row += NGW) {
;         f32x4* xr = (f32x4*)(h + (size_t)row * DM);
;         f32x4 v[4]; float s = 0.f;
; #pragma unroll
;         for (int j = 0; j < 4; ++j) { v[j] = xr[lane + 64 * j]; s += (v[j].x * v[j].x + v[j].y * v[j].y) + (v[j].z * v[j].z + v[j].w * v[j].w); }
;         const float r = rsqrtf(wave_sum(s) * (1.f / DM) + EPS);
; #pragma unroll
;         for (int j = 0; j < 4; ++j) xr[lane + 64 * j] = v[j] * r * wv[j];
;     }
.Lfinalnorm_procB:
	v_mul_f32_e32 v76, v60, v60
	v_mul_f32_e32 v77, v64, v64
	v_mul_f32_e32 v78, v68, v68
	v_mul_f32_e32 v79, v72, v72
	v_fmac_f32_e32 v76, v61, v61
	v_fmac_f32_e32 v77, v65, v65
	v_fmac_f32_e32 v78, v69, v69
	v_fmac_f32_e32 v79, v73, v73
	v_fmac_f32_e32 v76, v62, v62
	v_fmac_f32_e32 v77, v66, v66
	v_fmac_f32_e32 v78, v70, v70
	v_fmac_f32_e32 v79, v74, v74
	v_fmac_f32_e32 v76, v63, v63
	v_fmac_f32_e32 v77, v67, v67
	v_fmac_f32_e32 v78, v71, v71
	v_fmac_f32_e32 v79, v75, v75
	v_add_f32_e32 v76, v76, v77
	v_add_f32_e32 v78, v78, v79
	s_lshl_b64 s[16:17], s[14:15], 12
	v_add_f32_e32 v25, v76, v78
	ds_bpermute_b32 v42, v18, v25
	s_waitcnt lgkmcnt(0)
	v_add_f32_e32 v25, v25, v42
	ds_bpermute_b32 v42, v19, v25
	s_waitcnt lgkmcnt(0)
	v_add_f32_e32 v25, v25, v42
	ds_bpermute_b32 v42, v20, v25
	s_waitcnt lgkmcnt(0)
	v_add_f32_e32 v25, v25, v42
	ds_bpermute_b32 v42, v21, v25
	s_waitcnt lgkmcnt(0)
	v_add_f32_e32 v25, v25, v42
	ds_bpermute_b32 v42, v22, v25
	s_waitcnt lgkmcnt(0)
	v_add_f32_e32 v25, v25, v42
	ds_bpermute_b32 v42, v23, v25
	s_waitcnt lgkmcnt(0)
	v_add_f32_e32 v25, v25, v42
	v_fmamk_f32 v25, v25, 0x3a800000, v24
	v_cmp_gt_f32_e32 vcc, s21, v25
	v_mul_f32_e32 v42, 0x4b800000, v25
	v_lshl_add_u64 v[44:45], v[46:47], 0, s[16:17]
	s_nop 0
	v_cndmask_b32_e32 v25, v25, v42, vcc
	v_rsq_f32_e32 v25, v25
	s_nop 0
	v_mul_f32_e32 v42, 0x45800000, v25
	v_cndmask_b32_e32 v42, v25, v42, vcc
	v_pk_mul_f32 v[60:61], v[60:61], v[42:43] op_sel_hi:[1,0]
	v_pk_mul_f32 v[62:63], v[62:63], v[42:43] op_sel_hi:[1,0]
	v_pk_mul_f32 v[64:65], v[64:65], v[42:43] op_sel_hi:[1,0]
	v_pk_mul_f32 v[66:67], v[66:67], v[42:43] op_sel_hi:[1,0]
	v_pk_mul_f32 v[68:69], v[68:69], v[42:43] op_sel_hi:[1,0]
	v_pk_mul_f32 v[70:71], v[70:71], v[42:43] op_sel_hi:[1,0]
	v_pk_mul_f32 v[72:73], v[72:73], v[42:43] op_sel_hi:[1,0]
	v_pk_mul_f32 v[74:75], v[74:75], v[42:43] op_sel_hi:[1,0]
	v_pk_mul_f32 v[60:61], v[0:1], v[60:61]
	v_pk_mul_f32 v[62:63], v[2:3], v[62:63]
	v_pk_mul_f32 v[64:65], v[4:5], v[64:65]
	v_pk_mul_f32 v[66:67], v[6:7], v[66:67]
	v_pk_mul_f32 v[68:69], v[8:9], v[68:69]
	v_pk_mul_f32 v[70:71], v[10:11], v[70:71]
	v_pk_mul_f32 v[72:73], v[12:13], v[72:73]
	v_pk_mul_f32 v[74:75], v[14:15], v[74:75]
	global_store_dwordx4 v[44:45], v[60:63], off
	global_store_dwordx4 v[44:45], v[64:67], off offset:1024
	global_store_dwordx4 v[44:45], v[68:71], off offset:2048
	global_store_dwordx4 v[44:45], v[72:75], off offset:3072
	s_cmp_lg_u32 s20, 0
	s_cbranch_scc1 .Lfinalnorm_done
	s_add_u32 s0, s0, s88
	s_addc_u32 s1, s1, s89
	s_add_u32 s8, s8, s10
	s_addc_u32 s9, s9, s11
	s_cmp_lt_i32 s0, 0x8000
	s_cbranch_scc0 .Lfinalnorm_lastA
	s_mov_b64 s[18:19], s[8:9]
	s_mov_b64 s[14:15], s[0:1]
	global_load_dwordx4 v[60:63], v16, s[18:19]
	global_load_dwordx4 v[64:67], v16, s[18:19] offset:1024
	global_load_dwordx4 v[68:71], v16, s[18:19] offset:2048
	global_load_dwordx4 v[72:75], v16, s[18:19] offset:3072
	s_waitcnt vmcnt(8)
.Lfinalnorm_procA:
	v_mul_f32_e32 v76, v26, v26
	v_mul_f32_e32 v77, v30, v30
	v_mul_f32_e32 v78, v34, v34
	v_mul_f32_e32 v79, v38, v38
	v_fmac_f32_e32 v76, v27, v27
	v_fmac_f32_e32 v77, v31, v31
	v_fmac_f32_e32 v78, v35, v35
	v_fmac_f32_e32 v79, v39, v39
	v_fmac_f32_e32 v76, v28, v28
	v_fmac_f32_e32 v77, v32, v32
	v_fmac_f32_e32 v78, v36, v36
	v_fmac_f32_e32 v79, v40, v40
	v_fmac_f32_e32 v76, v29, v29
	v_fmac_f32_e32 v77, v33, v33
	v_fmac_f32_e32 v78, v37, v37
	v_fmac_f32_e32 v79, v41, v41
	v_add_f32_e32 v76, v76, v77
	v_add_f32_e32 v78, v78, v79
	s_lshl_b64 s[16:17], s[12:13], 12
	v_add_f32_e32 v25, v76, v78
	ds_bpermute_b32 v42, v18, v25
	s_waitcnt lgkmcnt(0)
	v_add_f32_e32 v25, v25, v42
	ds_bpermute_b32 v42, v19, v25
	s_waitcnt lgkmcnt(0)
	v_add_f32_e32 v25, v25, v42
	ds_bpermute_b32 v42, v20, v25
	s_waitcnt lgkmcnt(0)
	v_add_f32_e32 v25, v25, v42
	ds_bpermute_b32 v42, v21, v25
	s_waitcnt lgkmcnt(0)
	v_add_f32_e32 v25, v25, v42
	ds_bpermute_b32 v42, v22, v25
	s_waitcnt lgkmcnt(0)
	v_add_f32_e32 v25, v25, v42
	ds_bpermute_b32 v42, v23, v25
	s_waitcnt lgkmcnt(0)
	v_add_f32_e32 v25, v25, v42
	v_fmamk_f32 v25, v25, 0x3a800000, v24
	v_cmp_gt_f32_e32 vcc, s21, v25
	v_mul_f32_e32 v42, 0x4b800000, v25
	v_lshl_add_u64 v[44:45], v[46:47], 0, s[16:17]
	s_nop 0
	v_cndmask_b32_e32 v25, v25, v42, vcc
	v_rsq_f32_e32 v25, v25
	s_nop 0
	v_mul_f32_e32 v42, 0x45800000, v25
	v_cndmask_b32_e32 v42, v25, v42, vcc
	v_pk_mul_f32 v[26:27], v[26:27], v[42:43] op_sel_hi:[1,0]
	v_pk_mul_f32 v[28:29], v[28:29], v[42:43] op_sel_hi:[1,0]
	v_pk_mul_f32 v[30:31], v[30:31], v[42:43] op_sel_hi:[1,0]
	v_pk_mul_f32 v[32:33], v[32:33], v[42:43] op_sel_hi:[1,0]
	v_pk_mul_f32 v[34:35], v[34:35], v[42:43] op_sel_hi:[1,0]
	v_pk_mul_f32 v[36:37], v[36:37], v[42:43] op_sel_hi:[1,0]
	v_pk_mul_f32 v[38:39], v[38:39], v[42:43] op_sel_hi:[1,0]
	v_pk_mul_f32 v[40:41], v[40:41], v[42:43] op_sel_hi:[1,0]
	v_pk_mul_f32 v[26:27], v[0:1], v[26:27]
	v_pk_mul_f32 v[28:29], v[2:3], v[28:29]
	v_pk_mul_f32 v[30:31], v[4:5], v[30:31]
	v_pk_mul_f32 v[32:33], v[6:7], v[32:33]
	v_pk_mul_f32 v[34:35], v[8:9], v[34:35]
	v_pk_mul_f32 v[36:37], v[10:11], v[36:37]
	v_pk_mul_f32 v[38:39], v[12:13], v[38:39]
	v_pk_mul_f32 v[40:41], v[14:15], v[40:41]
	global_store_dwordx4 v[44:45], v[26:29], off
	global_store_dwordx4 v[44:45], v[30:33], off offset:1024
	global_store_dwordx4 v[44:45], v[34:37], off offset:2048
	global_store_dwordx4 v[44:45], v[38:41], off offset:3072
	s_cmp_lg_u32 s20, 0
	s_cbranch_scc1 .Lfinalnorm_done
	s_branch .Lfinalnorm_loop
.Lfinalnorm_lastB:
	s_mov_b32 s20, 1
	s_waitcnt vmcnt(4)
	s_branch .Lfinalnorm_procB

; __global__ void __launch_bounds__(NTHR, 2) hybrid_fwd(Args args) {
;     ...
;     {   PHASE_BEGIN
;         final_norm_phase(hreal, P->final_w, G); }
; }
.Lfinalnorm_done:
.LBB0_1130:
	s_endpgm
